# scan pass 2 state-chaining step: H row reads issued four steps ahead behind counted LDS waits
# speedup vs baseline: 1.0069x; 1.0019x over previous
; #define LAS __attribute__((address_space(3)))
; __device__ __forceinline__ void scan_pass2(const ScanP& sp, int b, int h, int seg, LAS unsigned char* lds) {
;     ...
;     for (int s = 0; s < seg; ++s) {
;         const float* HE = sp.HE + (size_t)((b * 8 + h) * 4 + s) * 4096; const float* PE = sp.PE + (size_t)((b * 8 + h) * 4 + s) * 4096;
;         f32x4 a0 = *(const f32x4*)(HE + j * 64 + i8), a1 = *(const f32x4*)(HE + j * 64 + i8 + 4);
;         f32x4 pvr[16];
; #pragma unroll
;         for (int jq = 0; jq < 16; ++jq) pvr[jq] = *(const f32x4*)(PE + j * 64 + 4 * jq);
; #pragma unroll
;         for (int jq = 0; jq < 16; ++jq) {
; #pragma unroll
;             for (int q = 0; q < 4; ++q) {
;                 const f32x4 h0 = *(const LAS f32x4*)(Hc + (4 * jq + q) * 64 + i8), h1 = *(const LAS f32x4*)(Hc + (4 * jq + q) * 64 + i8 + 4);
;                 a0 += h0 * pvr[jq][q]; a1 += h1 * pvr[jq][q];
;             }
;         }
.LBB0_338:
	v_lshl_add_u64 v[2:3], v[32:33], 0, v[0:1]
	global_load_dwordx4 v[38:41], v[2:3], off
	global_load_dwordx4 v[42:45], v[2:3], off offset:16
	v_add_co_u32_e32 v2, vcc, 0x400000, v32
	s_mov_b32 s6, s7
	s_nop 0
	v_addc_co_u32_e32 v3, vcc, 0, v33, vcc
	global_load_dwordx4 v[46:49], v[2:3], off
	global_load_dwordx4 v[50:53], v[2:3], off offset:16
	global_load_dwordx4 v[54:57], v[2:3], off offset:32
	global_load_dwordx4 v[58:61], v[2:3], off offset:48
	global_load_dwordx4 v[62:65], v[2:3], off offset:64
	global_load_dwordx4 v[66:69], v[2:3], off offset:80
	global_load_dwordx4 v[70:73], v[2:3], off offset:96
	global_load_dwordx4 v[74:77], v[2:3], off offset:112
	global_load_dwordx4 v[78:81], v[2:3], off offset:128
	global_load_dwordx4 v[26:29], v[2:3], off offset:144
	global_load_dwordx4 v[22:25], v[2:3], off offset:160
	global_load_dwordx4 v[18:21], v[2:3], off offset:176
	global_load_dwordx4 v[14:17], v[2:3], off offset:192
	global_load_dwordx4 v[10:13], v[2:3], off offset:208
	global_load_dwordx4 v[6:9], v[2:3], off offset:224
	s_nop 0
	global_load_dwordx4 v[2:5], v[2:3], off offset:240
	v_add_u32_e32 v31, s6, v37
	ds_read_b128 v[90:93], v31
	ds_read_b128 v[94:97], v31 offset:16
	ds_read_b128 v[106:109], v31 offset:256
	ds_read_b128 v[110:113], v31 offset:272
	ds_read_b128 v[114:117], v31 offset:512
	ds_read_b128 v[118:121], v31 offset:528
	ds_read_b128 v[122:125], v31 offset:768
	ds_read_b128 v[126:129], v31 offset:784
	s_mov_b32 s7, s5
	s_add_i32 s1, s1, -1
	s_mov_b64 s[8:9], 0x4000
	v_lshl_add_u64 v[32:33], v[32:33], 0, s[8:9]
	s_cmp_eq_u32 s1, 0
	s_mov_b32 s5, s6
	s_waitcnt vmcnt(0)
	s_waitcnt lgkmcnt(6)
	v_pk_fma_f32 v[82:83], v[46:47], v[90:91], v[38:39] op_sel_hi:[0,1,1]
	v_pk_fma_f32 v[84:85], v[46:47], v[92:93], v[40:41] op_sel_hi:[0,1,1]
	v_pk_fma_f32 v[86:87], v[46:47], v[94:95], v[42:43] op_sel_hi:[0,1,1]
	v_pk_fma_f32 v[88:89], v[46:47], v[96:97], v[44:45] op_sel_hi:[0,1,1]
	ds_read_b128 v[90:93], v31 offset:1024
	ds_read_b128 v[94:97], v31 offset:1040
	s_waitcnt lgkmcnt(6)
	v_pk_fma_f32 v[82:83], v[46:47], v[106:107], v[82:83] op_sel:[1,0,0]
	v_pk_fma_f32 v[84:85], v[46:47], v[108:109], v[84:85] op_sel:[1,0,0]
	v_pk_fma_f32 v[86:87], v[46:47], v[110:111], v[86:87] op_sel:[1,0,0]
	v_pk_fma_f32 v[88:89], v[46:47], v[112:113], v[88:89] op_sel:[1,0,0]
	ds_read_b128 v[106:109], v31 offset:1280
	ds_read_b128 v[110:113], v31 offset:1296
	s_waitcnt lgkmcnt(6)
	v_pk_fma_f32 v[82:83], v[48:49], v[114:115], v[82:83] op_sel_hi:[0,1,1]
	v_pk_fma_f32 v[84:85], v[48:49], v[116:117], v[84:85] op_sel_hi:[0,1,1]
	v_pk_fma_f32 v[86:87], v[48:49], v[118:119], v[86:87] op_sel_hi:[0,1,1]
	v_pk_fma_f32 v[88:89], v[48:49], v[120:121], v[88:89] op_sel_hi:[0,1,1]
	ds_read_b128 v[114:117], v31 offset:1536
	ds_read_b128 v[118:121], v31 offset:1552
	s_waitcnt lgkmcnt(6)
	v_pk_fma_f32 v[82:83], v[48:49], v[122:123], v[82:83] op_sel:[1,0,0]
	v_pk_fma_f32 v[84:85], v[48:49], v[124:125], v[84:85] op_sel:[1,0,0]
	v_pk_fma_f32 v[86:87], v[48:49], v[126:127], v[86:87] op_sel:[1,0,0]
	v_pk_fma_f32 v[88:89], v[48:49], v[128:129], v[88:89] op_sel:[1,0,0]
	ds_read_b128 v[122:125], v31 offset:1792
	ds_read_b128 v[126:129], v31 offset:1808
	s_waitcnt lgkmcnt(6)
	v_pk_fma_f32 v[82:83], v[50:51], v[90:91], v[82:83] op_sel_hi:[0,1,1]
	v_pk_fma_f32 v[84:85], v[50:51], v[92:93], v[84:85] op_sel_hi:[0,1,1]
	v_pk_fma_f32 v[86:87], v[50:51], v[94:95], v[86:87] op_sel_hi:[0,1,1]
	v_pk_fma_f32 v[88:89], v[50:51], v[96:97], v[88:89] op_sel_hi:[0,1,1]
	ds_read_b128 v[90:93], v31 offset:2048
	ds_read_b128 v[94:97], v31 offset:2064
	s_waitcnt lgkmcnt(6)
	v_pk_fma_f32 v[82:83], v[50:51], v[106:107], v[82:83] op_sel:[1,0,0]
	v_pk_fma_f32 v[84:85], v[50:51], v[108:109], v[84:85] op_sel:[1,0,0]
	v_pk_fma_f32 v[86:87], v[50:51], v[110:111], v[86:87] op_sel:[1,0,0]
	v_pk_fma_f32 v[88:89], v[50:51], v[112:113], v[88:89] op_sel:[1,0,0]
	ds_read_b128 v[106:109], v31 offset:2304
	ds_read_b128 v[110:113], v31 offset:2320
	s_waitcnt lgkmcnt(6)
	v_pk_fma_f32 v[82:83], v[52:53], v[114:115], v[82:83] op_sel_hi:[0,1,1]
	v_pk_fma_f32 v[84:85], v[52:53], v[116:117], v[84:85] op_sel_hi:[0,1,1]
	v_pk_fma_f32 v[86:87], v[52:53], v[118:119], v[86:87] op_sel_hi:[0,1,1]
	v_pk_fma_f32 v[88:89], v[52:53], v[120:121], v[88:89] op_sel_hi:[0,1,1]
	ds_read_b128 v[114:117], v31 offset:2560
	ds_read_b128 v[118:121], v31 offset:2576
	s_waitcnt lgkmcnt(6)
	v_pk_fma_f32 v[82:83], v[52:53], v[122:123], v[82:83] op_sel:[1,0,0]
	v_pk_fma_f32 v[84:85], v[52:53], v[124:125], v[84:85] op_sel:[1,0,0]
	v_pk_fma_f32 v[86:87], v[52:53], v[126:127], v[86:87] op_sel:[1,0,0]
	v_pk_fma_f32 v[88:89], v[52:53], v[128:129], v[88:89] op_sel:[1,0,0]
	ds_read_b128 v[122:125], v31 offset:2816
	ds_read_b128 v[126:129], v31 offset:2832
	s_waitcnt lgkmcnt(6)
	v_pk_fma_f32 v[82:83], v[54:55], v[90:91], v[82:83] op_sel_hi:[0,1,1]
	v_pk_fma_f32 v[84:85], v[54:55], v[92:93], v[84:85] op_sel_hi:[0,1,1]
	v_pk_fma_f32 v[86:87], v[54:55], v[94:95], v[86:87] op_sel_hi:[0,1,1]
	v_pk_fma_f32 v[88:89], v[54:55], v[96:97], v[88:89] op_sel_hi:[0,1,1]
	ds_read_b128 v[90:93], v31 offset:3072
	ds_read_b128 v[94:97], v31 offset:3088
	s_waitcnt lgkmcnt(6)
	v_pk_fma_f32 v[82:83], v[54:55], v[106:107], v[82:83] op_sel:[1,0,0]
	v_pk_fma_f32 v[84:85], v[54:55], v[108:109], v[84:85] op_sel:[1,0,0]
	v_pk_fma_f32 v[86:87], v[54:55], v[110:111], v[86:87] op_sel:[1,0,0]
	v_pk_fma_f32 v[88:89], v[54:55], v[112:113], v[88:89] op_sel:[1,0,0]
	ds_read_b128 v[106:109], v31 offset:3328
	ds_read_b128 v[110:113], v31 offset:3344
	s_waitcnt lgkmcnt(6)
; #define LAS __attribute__((address_space(3)))
; __device__ __forceinline__ void scan_pass2(const ScanP& sp, int b, int h, int seg, LAS unsigned char* lds) {
;     ...
;         for (int jq = 0; jq < 16; ++jq) {
; #pragma unroll
;             for (int q = 0; q < 4; ++q) {
;                 const f32x4 h0 = *(const LAS f32x4*)(Hc + (4 * jq + q) * 64 + i8), h1 = *(const LAS f32x4*)(Hc + (4 * jq + q) * 64 + i8 + 4);
;                 a0 += h0 * pvr[jq][q]; a1 += h1 * pvr[jq][q];
;             }
;         }
	v_pk_fma_f32 v[82:83], v[56:57], v[114:115], v[82:83] op_sel_hi:[0,1,1]
	v_pk_fma_f32 v[84:85], v[56:57], v[116:117], v[84:85] op_sel_hi:[0,1,1]
	v_pk_fma_f32 v[86:87], v[56:57], v[118:119], v[86:87] op_sel_hi:[0,1,1]
	v_pk_fma_f32 v[88:89], v[56:57], v[120:121], v[88:89] op_sel_hi:[0,1,1]
	ds_read_b128 v[114:117], v31 offset:3584
	ds_read_b128 v[118:121], v31 offset:3600
	s_waitcnt lgkmcnt(6)
	v_pk_fma_f32 v[82:83], v[56:57], v[122:123], v[82:83] op_sel:[1,0,0]
	v_pk_fma_f32 v[84:85], v[56:57], v[124:125], v[84:85] op_sel:[1,0,0]
	v_pk_fma_f32 v[86:87], v[56:57], v[126:127], v[86:87] op_sel:[1,0,0]
	v_pk_fma_f32 v[88:89], v[56:57], v[128:129], v[88:89] op_sel:[1,0,0]
	ds_read_b128 v[122:125], v31 offset:3840
	ds_read_b128 v[126:129], v31 offset:3856
	s_waitcnt lgkmcnt(6)
	v_pk_fma_f32 v[82:83], v[58:59], v[90:91], v[82:83] op_sel_hi:[0,1,1]
	v_pk_fma_f32 v[84:85], v[58:59], v[92:93], v[84:85] op_sel_hi:[0,1,1]
	v_pk_fma_f32 v[86:87], v[58:59], v[94:95], v[86:87] op_sel_hi:[0,1,1]
	v_pk_fma_f32 v[88:89], v[58:59], v[96:97], v[88:89] op_sel_hi:[0,1,1]
	ds_read_b128 v[90:93], v31 offset:4096
	ds_read_b128 v[94:97], v31 offset:4112
	s_waitcnt lgkmcnt(6)
	v_pk_fma_f32 v[82:83], v[58:59], v[106:107], v[82:83] op_sel:[1,0,0]
	v_pk_fma_f32 v[84:85], v[58:59], v[108:109], v[84:85] op_sel:[1,0,0]
	v_pk_fma_f32 v[86:87], v[58:59], v[110:111], v[86:87] op_sel:[1,0,0]
	v_pk_fma_f32 v[88:89], v[58:59], v[112:113], v[88:89] op_sel:[1,0,0]
	ds_read_b128 v[106:109], v31 offset:4352
	ds_read_b128 v[110:113], v31 offset:4368
	s_waitcnt lgkmcnt(6)
	v_pk_fma_f32 v[82:83], v[60:61], v[114:115], v[82:83] op_sel_hi:[0,1,1]
	v_pk_fma_f32 v[84:85], v[60:61], v[116:117], v[84:85] op_sel_hi:[0,1,1]
	v_pk_fma_f32 v[86:87], v[60:61], v[118:119], v[86:87] op_sel_hi:[0,1,1]
	v_pk_fma_f32 v[88:89], v[60:61], v[120:121], v[88:89] op_sel_hi:[0,1,1]
	ds_read_b128 v[114:117], v31 offset:4608
	ds_read_b128 v[118:121], v31 offset:4624
	s_waitcnt lgkmcnt(6)
	v_pk_fma_f32 v[82:83], v[60:61], v[122:123], v[82:83] op_sel:[1,0,0]
	v_pk_fma_f32 v[84:85], v[60:61], v[124:125], v[84:85] op_sel:[1,0,0]
	v_pk_fma_f32 v[86:87], v[60:61], v[126:127], v[86:87] op_sel:[1,0,0]
	v_pk_fma_f32 v[88:89], v[60:61], v[128:129], v[88:89] op_sel:[1,0,0]
	ds_read_b128 v[122:125], v31 offset:4864
	ds_read_b128 v[126:129], v31 offset:4880
	s_waitcnt lgkmcnt(6)
	v_pk_fma_f32 v[82:83], v[62:63], v[90:91], v[82:83] op_sel_hi:[0,1,1]
	v_pk_fma_f32 v[84:85], v[62:63], v[92:93], v[84:85] op_sel_hi:[0,1,1]
	v_pk_fma_f32 v[86:87], v[62:63], v[94:95], v[86:87] op_sel_hi:[0,1,1]
	v_pk_fma_f32 v[88:89], v[62:63], v[96:97], v[88:89] op_sel_hi:[0,1,1]
	ds_read_b128 v[90:93], v31 offset:5120
	ds_read_b128 v[94:97], v31 offset:5136
	s_waitcnt lgkmcnt(6)
	v_pk_fma_f32 v[82:83], v[62:63], v[106:107], v[82:83] op_sel:[1,0,0]
	v_pk_fma_f32 v[84:85], v[62:63], v[108:109], v[84:85] op_sel:[1,0,0]
	v_pk_fma_f32 v[86:87], v[62:63], v[110:111], v[86:87] op_sel:[1,0,0]
	v_pk_fma_f32 v[88:89], v[62:63], v[112:113], v[88:89] op_sel:[1,0,0]
	ds_read_b128 v[106:109], v31 offset:5376
	ds_read_b128 v[110:113], v31 offset:5392
	s_waitcnt lgkmcnt(6)
	v_pk_fma_f32 v[82:83], v[64:65], v[114:115], v[82:83] op_sel_hi:[0,1,1]
	v_pk_fma_f32 v[84:85], v[64:65], v[116:117], v[84:85] op_sel_hi:[0,1,1]
	v_pk_fma_f32 v[86:87], v[64:65], v[118:119], v[86:87] op_sel_hi:[0,1,1]
	v_pk_fma_f32 v[88:89], v[64:65], v[120:121], v[88:89] op_sel_hi:[0,1,1]
	ds_read_b128 v[114:117], v31 offset:5632
	ds_read_b128 v[118:121], v31 offset:5648
	s_waitcnt lgkmcnt(6)
	v_pk_fma_f32 v[82:83], v[64:65], v[122:123], v[82:83] op_sel:[1,0,0]
	v_pk_fma_f32 v[84:85], v[64:65], v[124:125], v[84:85] op_sel:[1,0,0]
	v_pk_fma_f32 v[86:87], v[64:65], v[126:127], v[86:87] op_sel:[1,0,0]
	v_pk_fma_f32 v[88:89], v[64:65], v[128:129], v[88:89] op_sel:[1,0,0]
	ds_read_b128 v[122:125], v31 offset:5888
	ds_read_b128 v[126:129], v31 offset:5904
	s_waitcnt lgkmcnt(6)
	v_pk_fma_f32 v[82:83], v[66:67], v[90:91], v[82:83] op_sel_hi:[0,1,1]
	v_pk_fma_f32 v[84:85], v[66:67], v[92:93], v[84:85] op_sel_hi:[0,1,1]
	v_pk_fma_f32 v[86:87], v[66:67], v[94:95], v[86:87] op_sel_hi:[0,1,1]
	v_pk_fma_f32 v[88:89], v[66:67], v[96:97], v[88:89] op_sel_hi:[0,1,1]
	ds_read_b128 v[90:93], v31 offset:6144
	ds_read_b128 v[94:97], v31 offset:6160
	s_waitcnt lgkmcnt(6)
	v_pk_fma_f32 v[82:83], v[66:67], v[106:107], v[82:83] op_sel:[1,0,0]
	v_pk_fma_f32 v[84:85], v[66:67], v[108:109], v[84:85] op_sel:[1,0,0]
	v_pk_fma_f32 v[86:87], v[66:67], v[110:111], v[86:87] op_sel:[1,0,0]
	v_pk_fma_f32 v[88:89], v[66:67], v[112:113], v[88:89] op_sel:[1,0,0]
	ds_read_b128 v[106:109], v31 offset:6400
	ds_read_b128 v[110:113], v31 offset:6416
	s_waitcnt lgkmcnt(6)
	v_pk_fma_f32 v[82:83], v[68:69], v[114:115], v[82:83] op_sel_hi:[0,1,1]
	v_pk_fma_f32 v[84:85], v[68:69], v[116:117], v[84:85] op_sel_hi:[0,1,1]
	v_pk_fma_f32 v[86:87], v[68:69], v[118:119], v[86:87] op_sel_hi:[0,1,1]
	v_pk_fma_f32 v[88:89], v[68:69], v[120:121], v[88:89] op_sel_hi:[0,1,1]
	ds_read_b128 v[114:117], v31 offset:6656
	ds_read_b128 v[118:121], v31 offset:6672
	s_waitcnt lgkmcnt(6)
	v_pk_fma_f32 v[82:83], v[68:69], v[122:123], v[82:83] op_sel:[1,0,0]
	v_pk_fma_f32 v[84:85], v[68:69], v[124:125], v[84:85] op_sel:[1,0,0]
	v_pk_fma_f32 v[86:87], v[68:69], v[126:127], v[86:87] op_sel:[1,0,0]
	v_pk_fma_f32 v[88:89], v[68:69], v[128:129], v[88:89] op_sel:[1,0,0]
	ds_read_b128 v[122:125], v31 offset:6912
	ds_read_b128 v[126:129], v31 offset:6928
	s_waitcnt lgkmcnt(6)
; #define LAS __attribute__((address_space(3)))
; __device__ __forceinline__ void scan_pass2(const ScanP& sp, int b, int h, int seg, LAS unsigned char* lds) {
;     ...
;         for (int jq = 0; jq < 16; ++jq) {
; #pragma unroll
;             for (int q = 0; q < 4; ++q) {
;                 const f32x4 h0 = *(const LAS f32x4*)(Hc + (4 * jq + q) * 64 + i8), h1 = *(const LAS f32x4*)(Hc + (4 * jq + q) * 64 + i8 + 4);
;                 a0 += h0 * pvr[jq][q]; a1 += h1 * pvr[jq][q];
;             }
;         }
	v_pk_fma_f32 v[82:83], v[70:71], v[90:91], v[82:83] op_sel_hi:[0,1,1]
	v_pk_fma_f32 v[84:85], v[70:71], v[92:93], v[84:85] op_sel_hi:[0,1,1]
	v_pk_fma_f32 v[86:87], v[70:71], v[94:95], v[86:87] op_sel_hi:[0,1,1]
	v_pk_fma_f32 v[88:89], v[70:71], v[96:97], v[88:89] op_sel_hi:[0,1,1]
	ds_read_b128 v[90:93], v31 offset:7168
	ds_read_b128 v[94:97], v31 offset:7184
	s_waitcnt lgkmcnt(6)
	v_pk_fma_f32 v[82:83], v[70:71], v[106:107], v[82:83] op_sel:[1,0,0]
	v_pk_fma_f32 v[84:85], v[70:71], v[108:109], v[84:85] op_sel:[1,0,0]
	v_pk_fma_f32 v[86:87], v[70:71], v[110:111], v[86:87] op_sel:[1,0,0]
	v_pk_fma_f32 v[88:89], v[70:71], v[112:113], v[88:89] op_sel:[1,0,0]
	ds_read_b128 v[106:109], v31 offset:7424
	ds_read_b128 v[110:113], v31 offset:7440
	s_waitcnt lgkmcnt(6)
	v_pk_fma_f32 v[82:83], v[72:73], v[114:115], v[82:83] op_sel_hi:[0,1,1]
	v_pk_fma_f32 v[84:85], v[72:73], v[116:117], v[84:85] op_sel_hi:[0,1,1]
	v_pk_fma_f32 v[86:87], v[72:73], v[118:119], v[86:87] op_sel_hi:[0,1,1]
	v_pk_fma_f32 v[88:89], v[72:73], v[120:121], v[88:89] op_sel_hi:[0,1,1]
	ds_read_b128 v[114:117], v31 offset:7680
	ds_read_b128 v[118:121], v31 offset:7696
	s_waitcnt lgkmcnt(6)
	v_pk_fma_f32 v[82:83], v[72:73], v[122:123], v[82:83] op_sel:[1,0,0]
	v_pk_fma_f32 v[84:85], v[72:73], v[124:125], v[84:85] op_sel:[1,0,0]
	v_pk_fma_f32 v[86:87], v[72:73], v[126:127], v[86:87] op_sel:[1,0,0]
	v_pk_fma_f32 v[88:89], v[72:73], v[128:129], v[88:89] op_sel:[1,0,0]
	ds_read_b128 v[122:125], v31 offset:7936
	ds_read_b128 v[126:129], v31 offset:7952
	s_waitcnt lgkmcnt(6)
	v_pk_fma_f32 v[82:83], v[74:75], v[90:91], v[82:83] op_sel_hi:[0,1,1]
	v_pk_fma_f32 v[84:85], v[74:75], v[92:93], v[84:85] op_sel_hi:[0,1,1]
	v_pk_fma_f32 v[86:87], v[74:75], v[94:95], v[86:87] op_sel_hi:[0,1,1]
	v_pk_fma_f32 v[88:89], v[74:75], v[96:97], v[88:89] op_sel_hi:[0,1,1]
	ds_read_b128 v[90:93], v31 offset:8192
	ds_read_b128 v[94:97], v31 offset:8208
	s_waitcnt lgkmcnt(6)
	v_pk_fma_f32 v[82:83], v[74:75], v[106:107], v[82:83] op_sel:[1,0,0]
	v_pk_fma_f32 v[84:85], v[74:75], v[108:109], v[84:85] op_sel:[1,0,0]
	v_pk_fma_f32 v[86:87], v[74:75], v[110:111], v[86:87] op_sel:[1,0,0]
	v_pk_fma_f32 v[88:89], v[74:75], v[112:113], v[88:89] op_sel:[1,0,0]
	ds_read_b128 v[106:109], v31 offset:8448
	ds_read_b128 v[110:113], v31 offset:8464
	s_waitcnt lgkmcnt(6)
	v_pk_fma_f32 v[82:83], v[76:77], v[114:115], v[82:83] op_sel_hi:[0,1,1]
	v_pk_fma_f32 v[84:85], v[76:77], v[116:117], v[84:85] op_sel_hi:[0,1,1]
	v_pk_fma_f32 v[86:87], v[76:77], v[118:119], v[86:87] op_sel_hi:[0,1,1]
	v_pk_fma_f32 v[88:89], v[76:77], v[120:121], v[88:89] op_sel_hi:[0,1,1]
	ds_read_b128 v[114:117], v31 offset:8704
	ds_read_b128 v[118:121], v31 offset:8720
	s_waitcnt lgkmcnt(6)
	v_pk_fma_f32 v[82:83], v[76:77], v[122:123], v[82:83] op_sel:[1,0,0]
	v_pk_fma_f32 v[84:85], v[76:77], v[124:125], v[84:85] op_sel:[1,0,0]
	v_pk_fma_f32 v[86:87], v[76:77], v[126:127], v[86:87] op_sel:[1,0,0]
	v_pk_fma_f32 v[88:89], v[76:77], v[128:129], v[88:89] op_sel:[1,0,0]
	ds_read_b128 v[122:125], v31 offset:8960
	ds_read_b128 v[126:129], v31 offset:8976
	s_waitcnt lgkmcnt(6)
	v_pk_fma_f32 v[82:83], v[78:79], v[90:91], v[82:83] op_sel_hi:[0,1,1]
	v_pk_fma_f32 v[84:85], v[78:79], v[92:93], v[84:85] op_sel_hi:[0,1,1]
	v_pk_fma_f32 v[86:87], v[78:79], v[94:95], v[86:87] op_sel_hi:[0,1,1]
	v_pk_fma_f32 v[88:89], v[78:79], v[96:97], v[88:89] op_sel_hi:[0,1,1]
	ds_read_b128 v[90:93], v31 offset:9216
	ds_read_b128 v[94:97], v31 offset:9232
	s_waitcnt lgkmcnt(6)
	v_pk_fma_f32 v[82:83], v[78:79], v[106:107], v[82:83] op_sel:[1,0,0]
	v_pk_fma_f32 v[84:85], v[78:79], v[108:109], v[84:85] op_sel:[1,0,0]
	v_pk_fma_f32 v[86:87], v[78:79], v[110:111], v[86:87] op_sel:[1,0,0]
	v_pk_fma_f32 v[88:89], v[78:79], v[112:113], v[88:89] op_sel:[1,0,0]
	ds_read_b128 v[106:109], v31 offset:9472
	ds_read_b128 v[110:113], v31 offset:9488
	s_waitcnt lgkmcnt(6)
	v_pk_fma_f32 v[82:83], v[80:81], v[114:115], v[82:83] op_sel_hi:[0,1,1]
	v_pk_fma_f32 v[84:85], v[80:81], v[116:117], v[84:85] op_sel_hi:[0,1,1]
	v_pk_fma_f32 v[86:87], v[80:81], v[118:119], v[86:87] op_sel_hi:[0,1,1]
	v_pk_fma_f32 v[88:89], v[80:81], v[120:121], v[88:89] op_sel_hi:[0,1,1]
	ds_read_b128 v[114:117], v31 offset:9728
	ds_read_b128 v[118:121], v31 offset:9744
	s_waitcnt lgkmcnt(6)
	v_pk_fma_f32 v[82:83], v[80:81], v[122:123], v[82:83] op_sel:[1,0,0]
	v_pk_fma_f32 v[84:85], v[80:81], v[124:125], v[84:85] op_sel:[1,0,0]
	v_pk_fma_f32 v[86:87], v[80:81], v[126:127], v[86:87] op_sel:[1,0,0]
	v_pk_fma_f32 v[88:89], v[80:81], v[128:129], v[88:89] op_sel:[1,0,0]
	ds_read_b128 v[122:125], v31 offset:9984
	ds_read_b128 v[126:129], v31 offset:10000
	s_waitcnt lgkmcnt(6)
	v_pk_fma_f32 v[82:83], v[26:27], v[90:91], v[82:83] op_sel_hi:[0,1,1]
	v_pk_fma_f32 v[84:85], v[26:27], v[92:93], v[84:85] op_sel_hi:[0,1,1]
	v_pk_fma_f32 v[86:87], v[26:27], v[94:95], v[86:87] op_sel_hi:[0,1,1]
	v_pk_fma_f32 v[88:89], v[26:27], v[96:97], v[88:89] op_sel_hi:[0,1,1]
	ds_read_b128 v[90:93], v31 offset:10240
	ds_read_b128 v[94:97], v31 offset:10256
	s_waitcnt lgkmcnt(6)
	v_pk_fma_f32 v[82:83], v[26:27], v[106:107], v[82:83] op_sel:[1,0,0]
	v_pk_fma_f32 v[84:85], v[26:27], v[108:109], v[84:85] op_sel:[1,0,0]
	v_pk_fma_f32 v[86:87], v[26:27], v[110:111], v[86:87] op_sel:[1,0,0]
	v_pk_fma_f32 v[88:89], v[26:27], v[112:113], v[88:89] op_sel:[1,0,0]
	ds_read_b128 v[106:109], v31 offset:10496
	ds_read_b128 v[110:113], v31 offset:10512
	s_waitcnt lgkmcnt(6)
; #define LAS __attribute__((address_space(3)))
; __device__ __forceinline__ void scan_pass2(const ScanP& sp, int b, int h, int seg, LAS unsigned char* lds) {
;     ...
;         for (int jq = 0; jq < 16; ++jq) {
; #pragma unroll
;             for (int q = 0; q < 4; ++q) {
;                 const f32x4 h0 = *(const LAS f32x4*)(Hc + (4 * jq + q) * 64 + i8), h1 = *(const LAS f32x4*)(Hc + (4 * jq + q) * 64 + i8 + 4);
;                 a0 += h0 * pvr[jq][q]; a1 += h1 * pvr[jq][q];
;             }
;         }
	v_pk_fma_f32 v[82:83], v[28:29], v[114:115], v[82:83] op_sel_hi:[0,1,1]
	v_pk_fma_f32 v[84:85], v[28:29], v[116:117], v[84:85] op_sel_hi:[0,1,1]
	v_pk_fma_f32 v[86:87], v[28:29], v[118:119], v[86:87] op_sel_hi:[0,1,1]
	v_pk_fma_f32 v[88:89], v[28:29], v[120:121], v[88:89] op_sel_hi:[0,1,1]
	ds_read_b128 v[114:117], v31 offset:10752
	ds_read_b128 v[118:121], v31 offset:10768
	s_waitcnt lgkmcnt(6)
	v_pk_fma_f32 v[82:83], v[28:29], v[122:123], v[82:83] op_sel:[1,0,0]
	v_pk_fma_f32 v[84:85], v[28:29], v[124:125], v[84:85] op_sel:[1,0,0]
	v_pk_fma_f32 v[86:87], v[28:29], v[126:127], v[86:87] op_sel:[1,0,0]
	v_pk_fma_f32 v[88:89], v[28:29], v[128:129], v[88:89] op_sel:[1,0,0]
	ds_read_b128 v[122:125], v31 offset:11008
	ds_read_b128 v[126:129], v31 offset:11024
	s_waitcnt lgkmcnt(6)
	v_pk_fma_f32 v[82:83], v[22:23], v[90:91], v[82:83] op_sel_hi:[0,1,1]
	v_pk_fma_f32 v[84:85], v[22:23], v[92:93], v[84:85] op_sel_hi:[0,1,1]
	v_pk_fma_f32 v[86:87], v[22:23], v[94:95], v[86:87] op_sel_hi:[0,1,1]
	v_pk_fma_f32 v[88:89], v[22:23], v[96:97], v[88:89] op_sel_hi:[0,1,1]
	ds_read_b128 v[90:93], v31 offset:11264
	ds_read_b128 v[94:97], v31 offset:11280
	s_waitcnt lgkmcnt(6)
	v_pk_fma_f32 v[82:83], v[22:23], v[106:107], v[82:83] op_sel:[1,0,0]
	v_pk_fma_f32 v[84:85], v[22:23], v[108:109], v[84:85] op_sel:[1,0,0]
	v_pk_fma_f32 v[86:87], v[22:23], v[110:111], v[86:87] op_sel:[1,0,0]
	v_pk_fma_f32 v[88:89], v[22:23], v[112:113], v[88:89] op_sel:[1,0,0]
	ds_read_b128 v[106:109], v31 offset:11520
	ds_read_b128 v[110:113], v31 offset:11536
	s_waitcnt lgkmcnt(6)
	v_pk_fma_f32 v[82:83], v[24:25], v[114:115], v[82:83] op_sel_hi:[0,1,1]
	v_pk_fma_f32 v[84:85], v[24:25], v[116:117], v[84:85] op_sel_hi:[0,1,1]
	v_pk_fma_f32 v[86:87], v[24:25], v[118:119], v[86:87] op_sel_hi:[0,1,1]
	v_pk_fma_f32 v[88:89], v[24:25], v[120:121], v[88:89] op_sel_hi:[0,1,1]
	ds_read_b128 v[114:117], v31 offset:11776
	ds_read_b128 v[118:121], v31 offset:11792
	s_waitcnt lgkmcnt(6)
	v_pk_fma_f32 v[82:83], v[24:25], v[122:123], v[82:83] op_sel:[1,0,0]
	v_pk_fma_f32 v[84:85], v[24:25], v[124:125], v[84:85] op_sel:[1,0,0]
	v_pk_fma_f32 v[86:87], v[24:25], v[126:127], v[86:87] op_sel:[1,0,0]
	v_pk_fma_f32 v[88:89], v[24:25], v[128:129], v[88:89] op_sel:[1,0,0]
	ds_read_b128 v[122:125], v31 offset:12032
	ds_read_b128 v[126:129], v31 offset:12048
	s_waitcnt lgkmcnt(6)
	v_pk_fma_f32 v[82:83], v[18:19], v[90:91], v[82:83] op_sel_hi:[0,1,1]
	v_pk_fma_f32 v[84:85], v[18:19], v[92:93], v[84:85] op_sel_hi:[0,1,1]
	v_pk_fma_f32 v[86:87], v[18:19], v[94:95], v[86:87] op_sel_hi:[0,1,1]
	v_pk_fma_f32 v[88:89], v[18:19], v[96:97], v[88:89] op_sel_hi:[0,1,1]
	ds_read_b128 v[90:93], v31 offset:12288
	ds_read_b128 v[94:97], v31 offset:12304
	s_waitcnt lgkmcnt(6)
	v_pk_fma_f32 v[82:83], v[18:19], v[106:107], v[82:83] op_sel:[1,0,0]
	v_pk_fma_f32 v[84:85], v[18:19], v[108:109], v[84:85] op_sel:[1,0,0]
	v_pk_fma_f32 v[86:87], v[18:19], v[110:111], v[86:87] op_sel:[1,0,0]
	v_pk_fma_f32 v[88:89], v[18:19], v[112:113], v[88:89] op_sel:[1,0,0]
	ds_read_b128 v[106:109], v31 offset:12544
	ds_read_b128 v[110:113], v31 offset:12560
	s_waitcnt lgkmcnt(6)
	v_pk_fma_f32 v[82:83], v[20:21], v[114:115], v[82:83] op_sel_hi:[0,1,1]
	v_pk_fma_f32 v[84:85], v[20:21], v[116:117], v[84:85] op_sel_hi:[0,1,1]
	v_pk_fma_f32 v[86:87], v[20:21], v[118:119], v[86:87] op_sel_hi:[0,1,1]
	v_pk_fma_f32 v[88:89], v[20:21], v[120:121], v[88:89] op_sel_hi:[0,1,1]
	ds_read_b128 v[114:117], v31 offset:12800
	ds_read_b128 v[118:121], v31 offset:12816
	s_waitcnt lgkmcnt(6)
	v_pk_fma_f32 v[82:83], v[20:21], v[122:123], v[82:83] op_sel:[1,0,0]
	v_pk_fma_f32 v[84:85], v[20:21], v[124:125], v[84:85] op_sel:[1,0,0]
	v_pk_fma_f32 v[86:87], v[20:21], v[126:127], v[86:87] op_sel:[1,0,0]
	v_pk_fma_f32 v[88:89], v[20:21], v[128:129], v[88:89] op_sel:[1,0,0]
	ds_read_b128 v[122:125], v31 offset:13056
	ds_read_b128 v[126:129], v31 offset:13072
	s_waitcnt lgkmcnt(6)
	v_pk_fma_f32 v[82:83], v[14:15], v[90:91], v[82:83] op_sel_hi:[0,1,1]
	v_pk_fma_f32 v[84:85], v[14:15], v[92:93], v[84:85] op_sel_hi:[0,1,1]
	v_pk_fma_f32 v[86:87], v[14:15], v[94:95], v[86:87] op_sel_hi:[0,1,1]
	v_pk_fma_f32 v[88:89], v[14:15], v[96:97], v[88:89] op_sel_hi:[0,1,1]
	ds_read_b128 v[90:93], v31 offset:13312
	ds_read_b128 v[94:97], v31 offset:13328
	s_waitcnt lgkmcnt(6)
	v_pk_fma_f32 v[82:83], v[14:15], v[106:107], v[82:83] op_sel:[1,0,0]
	v_pk_fma_f32 v[84:85], v[14:15], v[108:109], v[84:85] op_sel:[1,0,0]
	v_pk_fma_f32 v[86:87], v[14:15], v[110:111], v[86:87] op_sel:[1,0,0]
	v_pk_fma_f32 v[88:89], v[14:15], v[112:113], v[88:89] op_sel:[1,0,0]
	ds_read_b128 v[106:109], v31 offset:13568
	ds_read_b128 v[110:113], v31 offset:13584
	s_waitcnt lgkmcnt(6)
	v_pk_fma_f32 v[82:83], v[16:17], v[114:115], v[82:83] op_sel_hi:[0,1,1]
	v_pk_fma_f32 v[84:85], v[16:17], v[116:117], v[84:85] op_sel_hi:[0,1,1]
	v_pk_fma_f32 v[86:87], v[16:17], v[118:119], v[86:87] op_sel_hi:[0,1,1]
	v_pk_fma_f32 v[88:89], v[16:17], v[120:121], v[88:89] op_sel_hi:[0,1,1]
	ds_read_b128 v[114:117], v31 offset:13824
	ds_read_b128 v[118:121], v31 offset:13840
	s_waitcnt lgkmcnt(6)
; #define LAS __attribute__((address_space(3)))
; __device__ __forceinline__ void scan_pass2(const ScanP& sp, int b, int h, int seg, LAS unsigned char* lds) {
;     ...
;         for (int jq = 0; jq < 16; ++jq) {
; #pragma unroll
;             for (int q = 0; q < 4; ++q) {
;                 const f32x4 h0 = *(const LAS f32x4*)(Hc + (4 * jq + q) * 64 + i8), h1 = *(const LAS f32x4*)(Hc + (4 * jq + q) * 64 + i8 + 4);
;                 a0 += h0 * pvr[jq][q]; a1 += h1 * pvr[jq][q];
;             }
;         }
;         *(LAS f32x4*)(Hn + j * 64 + i8) = a0; *(LAS f32x4*)(Hn + j * 64 + i8 + 4) = a1;
;         __syncthreads();
;         LAS float* t_ = Hc; Hc = Hn; Hn = t_;
	v_pk_fma_f32 v[82:83], v[16:17], v[122:123], v[82:83] op_sel:[1,0,0]
	v_pk_fma_f32 v[84:85], v[16:17], v[124:125], v[84:85] op_sel:[1,0,0]
	v_pk_fma_f32 v[86:87], v[16:17], v[126:127], v[86:87] op_sel:[1,0,0]
	v_pk_fma_f32 v[88:89], v[16:17], v[128:129], v[88:89] op_sel:[1,0,0]
	ds_read_b128 v[122:125], v31 offset:14080
	ds_read_b128 v[126:129], v31 offset:14096
	s_waitcnt lgkmcnt(6)
	v_pk_fma_f32 v[82:83], v[10:11], v[90:91], v[82:83] op_sel_hi:[0,1,1]
	v_pk_fma_f32 v[84:85], v[10:11], v[92:93], v[84:85] op_sel_hi:[0,1,1]
	v_pk_fma_f32 v[86:87], v[10:11], v[94:95], v[86:87] op_sel_hi:[0,1,1]
	v_pk_fma_f32 v[88:89], v[10:11], v[96:97], v[88:89] op_sel_hi:[0,1,1]
	ds_read_b128 v[90:93], v31 offset:14336
	ds_read_b128 v[94:97], v31 offset:14352
	s_waitcnt lgkmcnt(6)
	v_pk_fma_f32 v[82:83], v[10:11], v[106:107], v[82:83] op_sel:[1,0,0]
	v_pk_fma_f32 v[84:85], v[10:11], v[108:109], v[84:85] op_sel:[1,0,0]
	v_pk_fma_f32 v[86:87], v[10:11], v[110:111], v[86:87] op_sel:[1,0,0]
	v_pk_fma_f32 v[88:89], v[10:11], v[112:113], v[88:89] op_sel:[1,0,0]
	ds_read_b128 v[106:109], v31 offset:14592
	ds_read_b128 v[110:113], v31 offset:14608
	s_waitcnt lgkmcnt(6)
	v_pk_fma_f32 v[82:83], v[12:13], v[114:115], v[82:83] op_sel_hi:[0,1,1]
	v_pk_fma_f32 v[84:85], v[12:13], v[116:117], v[84:85] op_sel_hi:[0,1,1]
	v_pk_fma_f32 v[86:87], v[12:13], v[118:119], v[86:87] op_sel_hi:[0,1,1]
	v_pk_fma_f32 v[88:89], v[12:13], v[120:121], v[88:89] op_sel_hi:[0,1,1]
	ds_read_b128 v[114:117], v31 offset:14848
	ds_read_b128 v[118:121], v31 offset:14864
	s_waitcnt lgkmcnt(6)
	v_pk_fma_f32 v[82:83], v[12:13], v[122:123], v[82:83] op_sel:[1,0,0]
	v_pk_fma_f32 v[84:85], v[12:13], v[124:125], v[84:85] op_sel:[1,0,0]
	v_pk_fma_f32 v[86:87], v[12:13], v[126:127], v[86:87] op_sel:[1,0,0]
	v_pk_fma_f32 v[88:89], v[12:13], v[128:129], v[88:89] op_sel:[1,0,0]
	ds_read_b128 v[122:125], v31 offset:15104
	ds_read_b128 v[126:129], v31 offset:15120
	s_waitcnt lgkmcnt(6)
	v_pk_fma_f32 v[82:83], v[6:7], v[90:91], v[82:83] op_sel_hi:[0,1,1]
	v_pk_fma_f32 v[84:85], v[6:7], v[92:93], v[84:85] op_sel_hi:[0,1,1]
	v_pk_fma_f32 v[86:87], v[6:7], v[94:95], v[86:87] op_sel_hi:[0,1,1]
	v_pk_fma_f32 v[88:89], v[6:7], v[96:97], v[88:89] op_sel_hi:[0,1,1]
	ds_read_b128 v[90:93], v31 offset:15360
	ds_read_b128 v[94:97], v31 offset:15376
	s_waitcnt lgkmcnt(6)
	v_pk_fma_f32 v[82:83], v[6:7], v[106:107], v[82:83] op_sel:[1,0,0]
	v_pk_fma_f32 v[84:85], v[6:7], v[108:109], v[84:85] op_sel:[1,0,0]
	v_pk_fma_f32 v[86:87], v[6:7], v[110:111], v[86:87] op_sel:[1,0,0]
	v_pk_fma_f32 v[88:89], v[6:7], v[112:113], v[88:89] op_sel:[1,0,0]
	ds_read_b128 v[106:109], v31 offset:15616
	ds_read_b128 v[110:113], v31 offset:15632
	s_waitcnt lgkmcnt(6)
	v_pk_fma_f32 v[82:83], v[8:9], v[114:115], v[82:83] op_sel_hi:[0,1,1]
	v_pk_fma_f32 v[84:85], v[8:9], v[116:117], v[84:85] op_sel_hi:[0,1,1]
	v_pk_fma_f32 v[86:87], v[8:9], v[118:119], v[86:87] op_sel_hi:[0,1,1]
	v_pk_fma_f32 v[88:89], v[8:9], v[120:121], v[88:89] op_sel_hi:[0,1,1]
	ds_read_b128 v[114:117], v31 offset:15872
	ds_read_b128 v[118:121], v31 offset:15888
	s_waitcnt lgkmcnt(6)
	v_pk_fma_f32 v[82:83], v[8:9], v[122:123], v[82:83] op_sel:[1,0,0]
	v_pk_fma_f32 v[84:85], v[8:9], v[124:125], v[84:85] op_sel:[1,0,0]
	v_pk_fma_f32 v[86:87], v[8:9], v[126:127], v[86:87] op_sel:[1,0,0]
	v_pk_fma_f32 v[88:89], v[8:9], v[128:129], v[88:89] op_sel:[1,0,0]
	ds_read_b128 v[122:125], v31 offset:16128
	ds_read_b128 v[126:129], v31 offset:16144
	s_waitcnt lgkmcnt(6)
	v_pk_fma_f32 v[82:83], v[2:3], v[90:91], v[82:83] op_sel_hi:[0,1,1]
	v_pk_fma_f32 v[84:85], v[2:3], v[92:93], v[84:85] op_sel_hi:[0,1,1]
	v_pk_fma_f32 v[86:87], v[2:3], v[94:95], v[86:87] op_sel_hi:[0,1,1]
	v_pk_fma_f32 v[88:89], v[2:3], v[96:97], v[88:89] op_sel_hi:[0,1,1]
	s_waitcnt lgkmcnt(4)
	v_pk_fma_f32 v[82:83], v[2:3], v[106:107], v[82:83] op_sel:[1,0,0]
	v_pk_fma_f32 v[84:85], v[2:3], v[108:109], v[84:85] op_sel:[1,0,0]
	v_pk_fma_f32 v[86:87], v[2:3], v[110:111], v[86:87] op_sel:[1,0,0]
	v_pk_fma_f32 v[88:89], v[2:3], v[112:113], v[88:89] op_sel:[1,0,0]
	s_waitcnt lgkmcnt(2)
	v_pk_fma_f32 v[82:83], v[4:5], v[114:115], v[82:83] op_sel_hi:[0,1,1]
	v_pk_fma_f32 v[84:85], v[4:5], v[116:117], v[84:85] op_sel_hi:[0,1,1]
	v_pk_fma_f32 v[86:87], v[4:5], v[118:119], v[86:87] op_sel_hi:[0,1,1]
	v_pk_fma_f32 v[88:89], v[4:5], v[120:121], v[88:89] op_sel_hi:[0,1,1]
	s_waitcnt lgkmcnt(0)
	v_pk_fma_f32 v[82:83], v[4:5], v[122:123], v[82:83] op_sel:[1,0,0]
	v_pk_fma_f32 v[84:85], v[4:5], v[124:125], v[84:85] op_sel:[1,0,0]
	v_pk_fma_f32 v[86:87], v[4:5], v[126:127], v[86:87] op_sel:[1,0,0]
	v_pk_fma_f32 v[88:89], v[4:5], v[128:129], v[88:89] op_sel:[1,0,0]
	v_mov_b64_e32 v[2:3], v[82:83]
	v_mov_b64_e32 v[4:5], v[84:85]
	v_mov_b64_e32 v[6:7], v[86:87]
	v_mov_b64_e32 v[8:9], v[88:89]
	v_lshlrev_b32_e32 v10, 2, v30
	v_add3_u32 v10, s7, v10, v37
	ds_write_b128 v10, v[2:5]
	ds_write_b128 v10, v[6:9] offset:16
	s_waitcnt lgkmcnt(0)
	s_barrier
	s_cbranch_scc0 .LBB0_338
